# misc routine: K split over 4 waves per 32-row unit (16 k-steps each), partial sums combined through LDS; all 8 waves of every workgroup busy
# baseline (speedup 1.0000x reference)
.LBB0_359:
	s_mov_b64 exec, -1
	v_readfirstlane_b32 s4, v190
	s_lshr_b32 s4, s4, 6
	v_readlane_b32 s48, v253, 14
	s_load_dwordx2 s[2:3], s[0:1], 0x100
	v_and_b32_e32 v0, 63, v190
	v_and_b32_e32 v1, 15, v0
	v_lshrrev_b32_e32 v3, 4, v0
	v_lshlrev_b32_e32 v3, 4, v3
	v_mul_u32_u24_e32 v2, 0x140, v1
	v_add_u32_e32 v2, v2, v3
	v_lshl_add_u32 v1, v1, 12, v3
	v_lshlrev_b32_e32 v5, 4, v0
	s_and_b32 s49, s4, 3
	s_lshr_b32 s50, s4, 2
	s_mul_i32 s6, s50, 0x7800
	v_add_u32_e32 v6, s6, v5
	s_add_i32 s7, s49, -1
	s_mul_i32 s7, s7, 0x2800
	s_add_i32 s7, s7, s6
	v_add_u32_e32 v5, s7, v5
	s_mov_b32 s24, 0
	s_waitcnt lgkmcnt(0)
.Lmisc_round:
	s_mov_b32 s44, 1
	s_lshl_b32 s5, s50, 8
	s_add_i32 s5, s5, s48
	s_cmp_eq_u32 s24, 0
	s_cbranch_scc1 .Lmisc_go
	s_add_i32 s5, s48, 0x200
	s_cmp_lt_u32 s4, 4
	s_cselect_b32 s44, 1, 0
	s_cbranch_scc0 .Lmisc_bar1
.Lmisc_go:
	s_lshl_b32 s6, s5, 17
	s_lshl_b32 s7, s49, 10
	s_add_u32 s8, s2, s6
	s_addc_u32 s9, s3, 0
	s_add_u32 s8, s8, s7
	s_addc_u32 s9, s9, 0
	s_add_u32 s8, s8, 0xe144d00
	s_addc_u32 s9, s9, 0
	s_add_u32 s16, s8, 0x10000
	s_addc_u32 s17, s9, 0
	s_add_u32 s18, s2, s7
	s_addc_u32 s19, s3, 0
	s_add_u32 s18, s18, 0x1000000
	s_addc_u32 s19, s19, 0
	s_add_u32 s28, s2, s7
	s_addc_u32 s29, s3, 0
	s_add_u32 s28, s28, 0x1010000
	s_addc_u32 s29, s29, 0
	s_add_u32 s30, s2, s7
	s_addc_u32 s31, s3, 0
	s_add_u32 s30, s30, 0x1020000
	s_addc_u32 s31, s31, 0
	s_add_u32 s34, s2, s7
	s_addc_u32 s35, s3, 0
	s_add_u32 s34, s34, 0x1030000
	s_addc_u32 s35, s35, 0
	s_add_u32 s36, s2, s7
	s_addc_u32 s37, s3, 0
	s_add_u32 s36, s36, 0x1040000
	s_addc_u32 s37, s37, 0
	v_mov_b64_e32 v[32:33], 0
	v_mov_b64_e32 v[34:35], 0
	v_mov_b64_e32 v[36:37], 0
	v_mov_b64_e32 v[38:39], 0
	v_mov_b64_e32 v[40:41], 0
	v_mov_b64_e32 v[42:43], 0
	v_mov_b64_e32 v[44:45], 0
	v_mov_b64_e32 v[46:47], 0
	v_mov_b64_e32 v[48:49], 0
	v_mov_b64_e32 v[50:51], 0
	v_mov_b64_e32 v[52:53], 0
	v_mov_b64_e32 v[54:55], 0
	v_mov_b64_e32 v[56:57], 0
	v_mov_b64_e32 v[58:59], 0
	v_mov_b64_e32 v[60:61], 0
	v_mov_b64_e32 v[62:63], 0
	v_mov_b64_e32 v[64:65], 0
	v_mov_b64_e32 v[66:67], 0
	v_mov_b64_e32 v[68:69], 0
	v_mov_b64_e32 v[70:71], 0
	global_load_dwordx4 v[72:75], v1, s[8:9]
	global_load_dwordx4 v[76:79], v1, s[16:17]
	global_load_dwordx4 v[80:83], v1, s[18:19]
	global_load_dwordx4 v[84:87], v1, s[28:29]
	global_load_dwordx4 v[88:91], v1, s[30:31]
	global_load_dwordx4 v[92:95], v1, s[34:35]
	global_load_dwordx4 v[96:99], v1, s[36:37]
	global_load_dwordx4 v[100:103], v1, s[8:9] offset:64
	global_load_dwordx4 v[104:107], v1, s[16:17] offset:64
	global_load_dwordx4 v[108:111], v1, s[18:19] offset:64
	global_load_dwordx4 v[112:115], v1, s[28:29] offset:64
	global_load_dwordx4 v[116:119], v1, s[30:31] offset:64
	global_load_dwordx4 v[120:123], v1, s[34:35] offset:64
	global_load_dwordx4 v[124:127], v1, s[36:37] offset:64
	global_load_dwordx4 v[128:131], v1, s[8:9] offset:128
	global_load_dwordx4 v[132:135], v1, s[16:17] offset:128
	global_load_dwordx4 v[136:139], v1, s[18:19] offset:128
	global_load_dwordx4 v[140:143], v1, s[28:29] offset:128
	global_load_dwordx4 v[144:147], v1, s[30:31] offset:128
	global_load_dwordx4 v[148:151], v1, s[34:35] offset:128
	global_load_dwordx4 v[152:155], v1, s[36:37] offset:128
	global_load_dwordx4 v[156:159], v1, s[8:9] offset:192
	global_load_dwordx4 v[172:175], v1, s[16:17] offset:192
	global_load_dwordx4 v[176:179], v1, s[18:19] offset:192
	global_load_dwordx4 v[180:183], v1, s[28:29] offset:192
	global_load_dwordx4 v[184:187], v1, s[30:31] offset:192
	global_load_dwordx4 v[196:199], v1, s[34:35] offset:192
	global_load_dwordx4 v[200:203], v1, s[36:37] offset:192
	global_load_dwordx4 v[204:207], v1, s[8:9] offset:256
	global_load_dwordx4 v[208:211], v1, s[16:17] offset:256
	global_load_dwordx4 v[212:215], v1, s[18:19] offset:256
	global_load_dwordx4 v[234:237], v1, s[28:29] offset:256
	global_load_dwordx4 v[238:241], v1, s[30:31] offset:256
	global_load_dwordx4 v[242:245], v1, s[34:35] offset:256
	global_load_dwordx4 v[246:249], v1, s[36:37] offset:256
	s_waitcnt vmcnt(28)
	v_mfma_f32_16x16x32_bf16 v[32:35], v[80:83], v[72:75], v[32:35]
	v_mfma_f32_16x16x32_bf16 v[52:55], v[80:83], v[76:79], v[52:55]
	v_mfma_f32_16x16x32_bf16 v[36:39], v[84:87], v[72:75], v[36:39]
	v_mfma_f32_16x16x32_bf16 v[56:59], v[84:87], v[76:79], v[56:59]
	v_mfma_f32_16x16x32_bf16 v[40:43], v[88:91], v[72:75], v[40:43]
	v_mfma_f32_16x16x32_bf16 v[60:63], v[88:91], v[76:79], v[60:63]
	v_mfma_f32_16x16x32_bf16 v[44:47], v[92:95], v[72:75], v[44:47]
	v_mfma_f32_16x16x32_bf16 v[64:67], v[92:95], v[76:79], v[64:67]
	v_mfma_f32_16x16x32_bf16 v[48:51], v[96:99], v[72:75], v[48:51]
	v_mfma_f32_16x16x32_bf16 v[68:71], v[96:99], v[76:79], v[68:71]
	global_load_dwordx4 v[72:75], v1, s[8:9] offset:320
	global_load_dwordx4 v[76:79], v1, s[16:17] offset:320
	global_load_dwordx4 v[80:83], v1, s[18:19] offset:320
	global_load_dwordx4 v[84:87], v1, s[28:29] offset:320
	global_load_dwordx4 v[88:91], v1, s[30:31] offset:320
	global_load_dwordx4 v[92:95], v1, s[34:35] offset:320
	global_load_dwordx4 v[96:99], v1, s[36:37] offset:320
	s_waitcnt vmcnt(28)
	v_mfma_f32_16x16x32_bf16 v[32:35], v[108:111], v[100:103], v[32:35]
	v_mfma_f32_16x16x32_bf16 v[52:55], v[108:111], v[104:107], v[52:55]
	v_mfma_f32_16x16x32_bf16 v[36:39], v[112:115], v[100:103], v[36:39]
	v_mfma_f32_16x16x32_bf16 v[56:59], v[112:115], v[104:107], v[56:59]
	v_mfma_f32_16x16x32_bf16 v[40:43], v[116:119], v[100:103], v[40:43]
	v_mfma_f32_16x16x32_bf16 v[60:63], v[116:119], v[104:107], v[60:63]
	v_mfma_f32_16x16x32_bf16 v[44:47], v[120:123], v[100:103], v[44:47]
	v_mfma_f32_16x16x32_bf16 v[64:67], v[120:123], v[104:107], v[64:67]
	v_mfma_f32_16x16x32_bf16 v[48:51], v[124:127], v[100:103], v[48:51]
	v_mfma_f32_16x16x32_bf16 v[68:71], v[124:127], v[104:107], v[68:71]
	global_load_dwordx4 v[100:103], v1, s[8:9] offset:384
	global_load_dwordx4 v[104:107], v1, s[16:17] offset:384
	global_load_dwordx4 v[108:111], v1, s[18:19] offset:384
	global_load_dwordx4 v[112:115], v1, s[28:29] offset:384
	global_load_dwordx4 v[116:119], v1, s[30:31] offset:384
	global_load_dwordx4 v[120:123], v1, s[34:35] offset:384
	global_load_dwordx4 v[124:127], v1, s[36:37] offset:384
	s_waitcnt vmcnt(28)
	v_mfma_f32_16x16x32_bf16 v[32:35], v[136:139], v[128:131], v[32:35]
	v_mfma_f32_16x16x32_bf16 v[52:55], v[136:139], v[132:135], v[52:55]
	v_mfma_f32_16x16x32_bf16 v[36:39], v[140:143], v[128:131], v[36:39]
	v_mfma_f32_16x16x32_bf16 v[56:59], v[140:143], v[132:135], v[56:59]
	v_mfma_f32_16x16x32_bf16 v[40:43], v[144:147], v[128:131], v[40:43]
	v_mfma_f32_16x16x32_bf16 v[60:63], v[144:147], v[132:135], v[60:63]
	v_mfma_f32_16x16x32_bf16 v[44:47], v[148:151], v[128:131], v[44:47]
	v_mfma_f32_16x16x32_bf16 v[64:67], v[148:151], v[132:135], v[64:67]
	v_mfma_f32_16x16x32_bf16 v[48:51], v[152:155], v[128:131], v[48:51]
	v_mfma_f32_16x16x32_bf16 v[68:71], v[152:155], v[132:135], v[68:71]
	global_load_dwordx4 v[128:131], v1, s[8:9] offset:448
	global_load_dwordx4 v[132:135], v1, s[16:17] offset:448
	global_load_dwordx4 v[136:139], v1, s[18:19] offset:448
	global_load_dwordx4 v[140:143], v1, s[28:29] offset:448
	global_load_dwordx4 v[144:147], v1, s[30:31] offset:448
	global_load_dwordx4 v[148:151], v1, s[34:35] offset:448
	global_load_dwordx4 v[152:155], v1, s[36:37] offset:448
	s_waitcnt vmcnt(28)
	v_mfma_f32_16x16x32_bf16 v[32:35], v[176:179], v[156:159], v[32:35]
	v_mfma_f32_16x16x32_bf16 v[52:55], v[176:179], v[172:175], v[52:55]
	v_mfma_f32_16x16x32_bf16 v[36:39], v[180:183], v[156:159], v[36:39]
	v_mfma_f32_16x16x32_bf16 v[56:59], v[180:183], v[172:175], v[56:59]
	v_mfma_f32_16x16x32_bf16 v[40:43], v[184:187], v[156:159], v[40:43]
	v_mfma_f32_16x16x32_bf16 v[60:63], v[184:187], v[172:175], v[60:63]
	v_mfma_f32_16x16x32_bf16 v[44:47], v[196:199], v[156:159], v[44:47]
	v_mfma_f32_16x16x32_bf16 v[64:67], v[196:199], v[172:175], v[64:67]
	v_mfma_f32_16x16x32_bf16 v[48:51], v[200:203], v[156:159], v[48:51]
	v_mfma_f32_16x16x32_bf16 v[68:71], v[200:203], v[172:175], v[68:71]
	global_load_dwordx4 v[156:159], v1, s[8:9] offset:512
	global_load_dwordx4 v[172:175], v1, s[16:17] offset:512
	global_load_dwordx4 v[176:179], v1, s[18:19] offset:512
	global_load_dwordx4 v[180:183], v1, s[28:29] offset:512
	global_load_dwordx4 v[184:187], v1, s[30:31] offset:512
	global_load_dwordx4 v[196:199], v1, s[34:35] offset:512
	global_load_dwordx4 v[200:203], v1, s[36:37] offset:512
	s_waitcnt vmcnt(28)
	v_mfma_f32_16x16x32_bf16 v[32:35], v[212:215], v[204:207], v[32:35]
	v_mfma_f32_16x16x32_bf16 v[52:55], v[212:215], v[208:211], v[52:55]
	v_mfma_f32_16x16x32_bf16 v[36:39], v[234:237], v[204:207], v[36:39]
	v_mfma_f32_16x16x32_bf16 v[56:59], v[234:237], v[208:211], v[56:59]
	v_mfma_f32_16x16x32_bf16 v[40:43], v[238:241], v[204:207], v[40:43]
	v_mfma_f32_16x16x32_bf16 v[60:63], v[238:241], v[208:211], v[60:63]
	v_mfma_f32_16x16x32_bf16 v[44:47], v[242:245], v[204:207], v[44:47]
	v_mfma_f32_16x16x32_bf16 v[64:67], v[242:245], v[208:211], v[64:67]
	v_mfma_f32_16x16x32_bf16 v[48:51], v[246:249], v[204:207], v[48:51]
	v_mfma_f32_16x16x32_bf16 v[68:71], v[246:249], v[208:211], v[68:71]
	global_load_dwordx4 v[204:207], v1, s[8:9] offset:576
	global_load_dwordx4 v[208:211], v1, s[16:17] offset:576
	global_load_dwordx4 v[212:215], v1, s[18:19] offset:576
	global_load_dwordx4 v[234:237], v1, s[28:29] offset:576
	global_load_dwordx4 v[238:241], v1, s[30:31] offset:576
	global_load_dwordx4 v[242:245], v1, s[34:35] offset:576
	global_load_dwordx4 v[246:249], v1, s[36:37] offset:576
	s_waitcnt vmcnt(28)
	v_mfma_f32_16x16x32_bf16 v[32:35], v[80:83], v[72:75], v[32:35]
	v_mfma_f32_16x16x32_bf16 v[52:55], v[80:83], v[76:79], v[52:55]
	v_mfma_f32_16x16x32_bf16 v[36:39], v[84:87], v[72:75], v[36:39]
	v_mfma_f32_16x16x32_bf16 v[56:59], v[84:87], v[76:79], v[56:59]
	v_mfma_f32_16x16x32_bf16 v[40:43], v[88:91], v[72:75], v[40:43]
	v_mfma_f32_16x16x32_bf16 v[60:63], v[88:91], v[76:79], v[60:63]
	v_mfma_f32_16x16x32_bf16 v[44:47], v[92:95], v[72:75], v[44:47]
	v_mfma_f32_16x16x32_bf16 v[64:67], v[92:95], v[76:79], v[64:67]
	v_mfma_f32_16x16x32_bf16 v[48:51], v[96:99], v[72:75], v[48:51]
	v_mfma_f32_16x16x32_bf16 v[68:71], v[96:99], v[76:79], v[68:71]
	global_load_dwordx4 v[72:75], v1, s[8:9] offset:640
	global_load_dwordx4 v[76:79], v1, s[16:17] offset:640
	global_load_dwordx4 v[80:83], v1, s[18:19] offset:640
	global_load_dwordx4 v[84:87], v1, s[28:29] offset:640
	global_load_dwordx4 v[88:91], v1, s[30:31] offset:640
	global_load_dwordx4 v[92:95], v1, s[34:35] offset:640
	global_load_dwordx4 v[96:99], v1, s[36:37] offset:640
	s_waitcnt vmcnt(28)
	v_mfma_f32_16x16x32_bf16 v[32:35], v[108:111], v[100:103], v[32:35]
	v_mfma_f32_16x16x32_bf16 v[52:55], v[108:111], v[104:107], v[52:55]
	v_mfma_f32_16x16x32_bf16 v[36:39], v[112:115], v[100:103], v[36:39]
	v_mfma_f32_16x16x32_bf16 v[56:59], v[112:115], v[104:107], v[56:59]
	v_mfma_f32_16x16x32_bf16 v[40:43], v[116:119], v[100:103], v[40:43]
	v_mfma_f32_16x16x32_bf16 v[60:63], v[116:119], v[104:107], v[60:63]
	v_mfma_f32_16x16x32_bf16 v[44:47], v[120:123], v[100:103], v[44:47]
	v_mfma_f32_16x16x32_bf16 v[64:67], v[120:123], v[104:107], v[64:67]
	v_mfma_f32_16x16x32_bf16 v[48:51], v[124:127], v[100:103], v[48:51]
	v_mfma_f32_16x16x32_bf16 v[68:71], v[124:127], v[104:107], v[68:71]
	global_load_dwordx4 v[100:103], v1, s[8:9] offset:704
	global_load_dwordx4 v[104:107], v1, s[16:17] offset:704
	global_load_dwordx4 v[108:111], v1, s[18:19] offset:704
	global_load_dwordx4 v[112:115], v1, s[28:29] offset:704
	global_load_dwordx4 v[116:119], v1, s[30:31] offset:704
	global_load_dwordx4 v[120:123], v1, s[34:35] offset:704
	global_load_dwordx4 v[124:127], v1, s[36:37] offset:704
	s_waitcnt vmcnt(28)
	v_mfma_f32_16x16x32_bf16 v[32:35], v[136:139], v[128:131], v[32:35]
	v_mfma_f32_16x16x32_bf16 v[52:55], v[136:139], v[132:135], v[52:55]
	v_mfma_f32_16x16x32_bf16 v[36:39], v[140:143], v[128:131], v[36:39]
	v_mfma_f32_16x16x32_bf16 v[56:59], v[140:143], v[132:135], v[56:59]
	v_mfma_f32_16x16x32_bf16 v[40:43], v[144:147], v[128:131], v[40:43]
	v_mfma_f32_16x16x32_bf16 v[60:63], v[144:147], v[132:135], v[60:63]
	v_mfma_f32_16x16x32_bf16 v[44:47], v[148:151], v[128:131], v[44:47]
	v_mfma_f32_16x16x32_bf16 v[64:67], v[148:151], v[132:135], v[64:67]
	v_mfma_f32_16x16x32_bf16 v[48:51], v[152:155], v[128:131], v[48:51]
	v_mfma_f32_16x16x32_bf16 v[68:71], v[152:155], v[132:135], v[68:71]
	global_load_dwordx4 v[128:131], v1, s[8:9] offset:768
	global_load_dwordx4 v[132:135], v1, s[16:17] offset:768
	global_load_dwordx4 v[136:139], v1, s[18:19] offset:768
	global_load_dwordx4 v[140:143], v1, s[28:29] offset:768
	global_load_dwordx4 v[144:147], v1, s[30:31] offset:768
	global_load_dwordx4 v[148:151], v1, s[34:35] offset:768
	global_load_dwordx4 v[152:155], v1, s[36:37] offset:768
	s_waitcnt vmcnt(28)
	v_mfma_f32_16x16x32_bf16 v[32:35], v[176:179], v[156:159], v[32:35]
	v_mfma_f32_16x16x32_bf16 v[52:55], v[176:179], v[172:175], v[52:55]
	v_mfma_f32_16x16x32_bf16 v[36:39], v[180:183], v[156:159], v[36:39]
	v_mfma_f32_16x16x32_bf16 v[56:59], v[180:183], v[172:175], v[56:59]
	v_mfma_f32_16x16x32_bf16 v[40:43], v[184:187], v[156:159], v[40:43]
	v_mfma_f32_16x16x32_bf16 v[60:63], v[184:187], v[172:175], v[60:63]
	v_mfma_f32_16x16x32_bf16 v[44:47], v[196:199], v[156:159], v[44:47]
	v_mfma_f32_16x16x32_bf16 v[64:67], v[196:199], v[172:175], v[64:67]
	v_mfma_f32_16x16x32_bf16 v[48:51], v[200:203], v[156:159], v[48:51]
	v_mfma_f32_16x16x32_bf16 v[68:71], v[200:203], v[172:175], v[68:71]
	global_load_dwordx4 v[156:159], v1, s[8:9] offset:832
	global_load_dwordx4 v[172:175], v1, s[16:17] offset:832
	global_load_dwordx4 v[176:179], v1, s[18:19] offset:832
	global_load_dwordx4 v[180:183], v1, s[28:29] offset:832
	global_load_dwordx4 v[184:187], v1, s[30:31] offset:832
	global_load_dwordx4 v[196:199], v1, s[34:35] offset:832
	global_load_dwordx4 v[200:203], v1, s[36:37] offset:832
	s_waitcnt vmcnt(28)
	v_mfma_f32_16x16x32_bf16 v[32:35], v[212:215], v[204:207], v[32:35]
	v_mfma_f32_16x16x32_bf16 v[52:55], v[212:215], v[208:211], v[52:55]
	v_mfma_f32_16x16x32_bf16 v[36:39], v[234:237], v[204:207], v[36:39]
	v_mfma_f32_16x16x32_bf16 v[56:59], v[234:237], v[208:211], v[56:59]
	v_mfma_f32_16x16x32_bf16 v[40:43], v[238:241], v[204:207], v[40:43]
	v_mfma_f32_16x16x32_bf16 v[60:63], v[238:241], v[208:211], v[60:63]
	v_mfma_f32_16x16x32_bf16 v[44:47], v[242:245], v[204:207], v[44:47]
	v_mfma_f32_16x16x32_bf16 v[64:67], v[242:245], v[208:211], v[64:67]
	v_mfma_f32_16x16x32_bf16 v[48:51], v[246:249], v[204:207], v[48:51]
	v_mfma_f32_16x16x32_bf16 v[68:71], v[246:249], v[208:211], v[68:71]
	global_load_dwordx4 v[204:207], v1, s[8:9] offset:896
	global_load_dwordx4 v[208:211], v1, s[16:17] offset:896
	global_load_dwordx4 v[212:215], v1, s[18:19] offset:896
	global_load_dwordx4 v[234:237], v1, s[28:29] offset:896
	global_load_dwordx4 v[238:241], v1, s[30:31] offset:896
	global_load_dwordx4 v[242:245], v1, s[34:35] offset:896
	global_load_dwordx4 v[246:249], v1, s[36:37] offset:896
	s_waitcnt vmcnt(28)
	v_mfma_f32_16x16x32_bf16 v[32:35], v[80:83], v[72:75], v[32:35]
	v_mfma_f32_16x16x32_bf16 v[52:55], v[80:83], v[76:79], v[52:55]
	v_mfma_f32_16x16x32_bf16 v[36:39], v[84:87], v[72:75], v[36:39]
	v_mfma_f32_16x16x32_bf16 v[56:59], v[84:87], v[76:79], v[56:59]
	v_mfma_f32_16x16x32_bf16 v[40:43], v[88:91], v[72:75], v[40:43]
	v_mfma_f32_16x16x32_bf16 v[60:63], v[88:91], v[76:79], v[60:63]
	v_mfma_f32_16x16x32_bf16 v[44:47], v[92:95], v[72:75], v[44:47]
	v_mfma_f32_16x16x32_bf16 v[64:67], v[92:95], v[76:79], v[64:67]
	v_mfma_f32_16x16x32_bf16 v[48:51], v[96:99], v[72:75], v[48:51]
	v_mfma_f32_16x16x32_bf16 v[68:71], v[96:99], v[76:79], v[68:71]
	global_load_dwordx4 v[72:75], v1, s[8:9] offset:960
	global_load_dwordx4 v[76:79], v1, s[16:17] offset:960
	global_load_dwordx4 v[80:83], v1, s[18:19] offset:960
	global_load_dwordx4 v[84:87], v1, s[28:29] offset:960
	global_load_dwordx4 v[88:91], v1, s[30:31] offset:960
	global_load_dwordx4 v[92:95], v1, s[34:35] offset:960
	global_load_dwordx4 v[96:99], v1, s[36:37] offset:960
	s_waitcnt vmcnt(28)
	v_mfma_f32_16x16x32_bf16 v[32:35], v[108:111], v[100:103], v[32:35]
	v_mfma_f32_16x16x32_bf16 v[52:55], v[108:111], v[104:107], v[52:55]
	v_mfma_f32_16x16x32_bf16 v[36:39], v[112:115], v[100:103], v[36:39]
	v_mfma_f32_16x16x32_bf16 v[56:59], v[112:115], v[104:107], v[56:59]
	v_mfma_f32_16x16x32_bf16 v[40:43], v[116:119], v[100:103], v[40:43]
	v_mfma_f32_16x16x32_bf16 v[60:63], v[116:119], v[104:107], v[60:63]
	v_mfma_f32_16x16x32_bf16 v[44:47], v[120:123], v[100:103], v[44:47]
	v_mfma_f32_16x16x32_bf16 v[64:67], v[120:123], v[104:107], v[64:67]
	v_mfma_f32_16x16x32_bf16 v[48:51], v[124:127], v[100:103], v[48:51]
	v_mfma_f32_16x16x32_bf16 v[68:71], v[124:127], v[104:107], v[68:71]
	s_waitcnt vmcnt(21)
	v_mfma_f32_16x16x32_bf16 v[32:35], v[136:139], v[128:131], v[32:35]
	v_mfma_f32_16x16x32_bf16 v[52:55], v[136:139], v[132:135], v[52:55]
	v_mfma_f32_16x16x32_bf16 v[36:39], v[140:143], v[128:131], v[36:39]
	v_mfma_f32_16x16x32_bf16 v[56:59], v[140:143], v[132:135], v[56:59]
	v_mfma_f32_16x16x32_bf16 v[40:43], v[144:147], v[128:131], v[40:43]
	v_mfma_f32_16x16x32_bf16 v[60:63], v[144:147], v[132:135], v[60:63]
	v_mfma_f32_16x16x32_bf16 v[44:47], v[148:151], v[128:131], v[44:47]
	v_mfma_f32_16x16x32_bf16 v[64:67], v[148:151], v[132:135], v[64:67]
	v_mfma_f32_16x16x32_bf16 v[48:51], v[152:155], v[128:131], v[48:51]
	v_mfma_f32_16x16x32_bf16 v[68:71], v[152:155], v[132:135], v[68:71]
	s_waitcnt vmcnt(14)
	v_mfma_f32_16x16x32_bf16 v[32:35], v[176:179], v[156:159], v[32:35]
	v_mfma_f32_16x16x32_bf16 v[52:55], v[176:179], v[172:175], v[52:55]
	v_mfma_f32_16x16x32_bf16 v[36:39], v[180:183], v[156:159], v[36:39]
	v_mfma_f32_16x16x32_bf16 v[56:59], v[180:183], v[172:175], v[56:59]
	v_mfma_f32_16x16x32_bf16 v[40:43], v[184:187], v[156:159], v[40:43]
	v_mfma_f32_16x16x32_bf16 v[60:63], v[184:187], v[172:175], v[60:63]
	v_mfma_f32_16x16x32_bf16 v[44:47], v[196:199], v[156:159], v[44:47]
	v_mfma_f32_16x16x32_bf16 v[64:67], v[196:199], v[172:175], v[64:67]
	v_mfma_f32_16x16x32_bf16 v[48:51], v[200:203], v[156:159], v[48:51]
	v_mfma_f32_16x16x32_bf16 v[68:71], v[200:203], v[172:175], v[68:71]
	s_waitcnt vmcnt(7)
	v_mfma_f32_16x16x32_bf16 v[32:35], v[212:215], v[204:207], v[32:35]
	v_mfma_f32_16x16x32_bf16 v[52:55], v[212:215], v[208:211], v[52:55]
	v_mfma_f32_16x16x32_bf16 v[36:39], v[234:237], v[204:207], v[36:39]
	v_mfma_f32_16x16x32_bf16 v[56:59], v[234:237], v[208:211], v[56:59]
	v_mfma_f32_16x16x32_bf16 v[40:43], v[238:241], v[204:207], v[40:43]
	v_mfma_f32_16x16x32_bf16 v[60:63], v[238:241], v[208:211], v[60:63]
	v_mfma_f32_16x16x32_bf16 v[44:47], v[242:245], v[204:207], v[44:47]
	v_mfma_f32_16x16x32_bf16 v[64:67], v[242:245], v[208:211], v[64:67]
	v_mfma_f32_16x16x32_bf16 v[48:51], v[246:249], v[204:207], v[48:51]
	v_mfma_f32_16x16x32_bf16 v[68:71], v[246:249], v[208:211], v[68:71]
	s_waitcnt vmcnt(0)
	v_mfma_f32_16x16x32_bf16 v[32:35], v[80:83], v[72:75], v[32:35]
	v_mfma_f32_16x16x32_bf16 v[52:55], v[80:83], v[76:79], v[52:55]
	v_mfma_f32_16x16x32_bf16 v[36:39], v[84:87], v[72:75], v[36:39]
	v_mfma_f32_16x16x32_bf16 v[56:59], v[84:87], v[76:79], v[56:59]
	v_mfma_f32_16x16x32_bf16 v[40:43], v[88:91], v[72:75], v[40:43]
	v_mfma_f32_16x16x32_bf16 v[60:63], v[88:91], v[76:79], v[60:63]
	v_mfma_f32_16x16x32_bf16 v[44:47], v[92:95], v[72:75], v[44:47]
	v_mfma_f32_16x16x32_bf16 v[64:67], v[92:95], v[76:79], v[64:67]
	v_mfma_f32_16x16x32_bf16 v[48:51], v[96:99], v[72:75], v[48:51]
	v_mfma_f32_16x16x32_bf16 v[68:71], v[96:99], v[76:79], v[68:71]
	s_cmp_eq_u32 s49, 0
	s_cbranch_scc1 .Lmisc_bar1
	s_nop 7
	ds_write_b128 v5, v[32:35]
	ds_write_b128 v5, v[36:39] offset:1024
	ds_write_b128 v5, v[40:43] offset:2048
	ds_write_b128 v5, v[44:47] offset:3072
	ds_write_b128 v5, v[48:51] offset:4096
	ds_write_b128 v5, v[52:55] offset:5120
	ds_write_b128 v5, v[56:59] offset:6144
	ds_write_b128 v5, v[60:63] offset:7168
	ds_write_b128 v5, v[64:67] offset:8192
	ds_write_b128 v5, v[68:71] offset:9216
.Lmisc_bar1:
	s_waitcnt lgkmcnt(0)
	s_barrier
	s_cmp_eq_u32 s44, 0
	s_cbranch_scc1 .Lmisc_bar2
	s_cmp_lg_u32 s49, 0
	s_cbranch_scc1 .Lmisc_bar2
	s_add_u32 s38, s2, 0x8884000
	s_addc_u32 s39, s3, 0
	s_mul_i32 s6, s5, 0x2800
	s_add_u32 s40, s2, s6
	s_addc_u32 s41, s3, 0
	s_add_u32 s40, s40, 0x21344d00
	s_addc_u32 s41, s41, 0
	s_add_u32 s46, s40, 0x1400
	s_addc_u32 s47, s41, 0
	global_load_dwordx4 v[172:175], v3, s[38:39]
	global_load_dwordx4 v[176:179], v3, s[38:39] offset:64
	global_load_dwordx4 v[180:183], v3, s[38:39] offset:128
	global_load_dwordx4 v[184:187], v3, s[38:39] offset:192
	global_load_dwordx4 v[196:199], v3, s[38:39] offset:256
	s_nop 7
	ds_read_b128 v[72:75], v6 offset:0
	ds_read_b128 v[76:79], v6 offset:1024
	ds_read_b128 v[80:83], v6 offset:2048
	ds_read_b128 v[84:87], v6 offset:3072
	ds_read_b128 v[88:91], v6 offset:4096
	ds_read_b128 v[92:95], v6 offset:5120
	ds_read_b128 v[96:99], v6 offset:6144
	ds_read_b128 v[100:103], v6 offset:7168
	ds_read_b128 v[104:107], v6 offset:8192
	ds_read_b128 v[108:111], v6 offset:9216
	s_waitcnt lgkmcnt(0)
	v_add_f32_e32 v32, v32, v72
	v_add_f32_e32 v33, v33, v73
	v_add_f32_e32 v34, v34, v74
	v_add_f32_e32 v35, v35, v75
	v_add_f32_e32 v36, v36, v76
	v_add_f32_e32 v37, v37, v77
	v_add_f32_e32 v38, v38, v78
	v_add_f32_e32 v39, v39, v79
	v_add_f32_e32 v40, v40, v80
	v_add_f32_e32 v41, v41, v81
	v_add_f32_e32 v42, v42, v82
	v_add_f32_e32 v43, v43, v83
	v_add_f32_e32 v44, v44, v84
	v_add_f32_e32 v45, v45, v85
	v_add_f32_e32 v46, v46, v86
	v_add_f32_e32 v47, v47, v87
	v_add_f32_e32 v48, v48, v88
	v_add_f32_e32 v49, v49, v89
	v_add_f32_e32 v50, v50, v90
	v_add_f32_e32 v51, v51, v91
	v_add_f32_e32 v52, v52, v92
	v_add_f32_e32 v53, v53, v93
	v_add_f32_e32 v54, v54, v94
	v_add_f32_e32 v55, v55, v95
	v_add_f32_e32 v56, v56, v96
	v_add_f32_e32 v57, v57, v97
	v_add_f32_e32 v58, v58, v98
	v_add_f32_e32 v59, v59, v99
	v_add_f32_e32 v60, v60, v100
	v_add_f32_e32 v61, v61, v101
	v_add_f32_e32 v62, v62, v102
	v_add_f32_e32 v63, v63, v103
	v_add_f32_e32 v64, v64, v104
	v_add_f32_e32 v65, v65, v105
	v_add_f32_e32 v66, v66, v106
	v_add_f32_e32 v67, v67, v107
	v_add_f32_e32 v68, v68, v108
	v_add_f32_e32 v69, v69, v109
	v_add_f32_e32 v70, v70, v110
	v_add_f32_e32 v71, v71, v111
	ds_read_b128 v[72:75], v6 offset:10240
	ds_read_b128 v[76:79], v6 offset:11264
	ds_read_b128 v[80:83], v6 offset:12288
	ds_read_b128 v[84:87], v6 offset:13312
	ds_read_b128 v[88:91], v6 offset:14336
	ds_read_b128 v[92:95], v6 offset:15360
	ds_read_b128 v[96:99], v6 offset:16384
	ds_read_b128 v[100:103], v6 offset:17408
	ds_read_b128 v[104:107], v6 offset:18432
	ds_read_b128 v[108:111], v6 offset:19456
	s_waitcnt lgkmcnt(0)
	v_add_f32_e32 v32, v32, v72
	v_add_f32_e32 v33, v33, v73
	v_add_f32_e32 v34, v34, v74
	v_add_f32_e32 v35, v35, v75
	v_add_f32_e32 v36, v36, v76
	v_add_f32_e32 v37, v37, v77
	v_add_f32_e32 v38, v38, v78
	v_add_f32_e32 v39, v39, v79
	v_add_f32_e32 v40, v40, v80
	v_add_f32_e32 v41, v41, v81
	v_add_f32_e32 v42, v42, v82
	v_add_f32_e32 v43, v43, v83
	v_add_f32_e32 v44, v44, v84
	v_add_f32_e32 v45, v45, v85
	v_add_f32_e32 v46, v46, v86
	v_add_f32_e32 v47, v47, v87
	v_add_f32_e32 v48, v48, v88
	v_add_f32_e32 v49, v49, v89
	v_add_f32_e32 v50, v50, v90
	v_add_f32_e32 v51, v51, v91
	v_add_f32_e32 v52, v52, v92
	v_add_f32_e32 v53, v53, v93
	v_add_f32_e32 v54, v54, v94
	v_add_f32_e32 v55, v55, v95
	v_add_f32_e32 v56, v56, v96
	v_add_f32_e32 v57, v57, v97
	v_add_f32_e32 v58, v58, v98
	v_add_f32_e32 v59, v59, v99
	v_add_f32_e32 v60, v60, v100
	v_add_f32_e32 v61, v61, v101
	v_add_f32_e32 v62, v62, v102
	v_add_f32_e32 v63, v63, v103
	v_add_f32_e32 v64, v64, v104
	v_add_f32_e32 v65, v65, v105
	v_add_f32_e32 v66, v66, v106
	v_add_f32_e32 v67, v67, v107
	v_add_f32_e32 v68, v68, v108
	v_add_f32_e32 v69, v69, v109
	v_add_f32_e32 v70, v70, v110
	v_add_f32_e32 v71, v71, v111
	ds_read_b128 v[72:75], v6 offset:20480
	ds_read_b128 v[76:79], v6 offset:21504
	ds_read_b128 v[80:83], v6 offset:22528
	ds_read_b128 v[84:87], v6 offset:23552
	ds_read_b128 v[88:91], v6 offset:24576
	ds_read_b128 v[92:95], v6 offset:25600
	ds_read_b128 v[96:99], v6 offset:26624
	ds_read_b128 v[100:103], v6 offset:27648
	ds_read_b128 v[104:107], v6 offset:28672
	ds_read_b128 v[108:111], v6 offset:29696
	s_waitcnt lgkmcnt(0)
	v_add_f32_e32 v32, v32, v72
	v_add_f32_e32 v33, v33, v73
	v_add_f32_e32 v34, v34, v74
	v_add_f32_e32 v35, v35, v75
	v_add_f32_e32 v36, v36, v76
	v_add_f32_e32 v37, v37, v77
	v_add_f32_e32 v38, v38, v78
	v_add_f32_e32 v39, v39, v79
	v_add_f32_e32 v40, v40, v80
	v_add_f32_e32 v41, v41, v81
	v_add_f32_e32 v42, v42, v82
	v_add_f32_e32 v43, v43, v83
	v_add_f32_e32 v44, v44, v84
	v_add_f32_e32 v45, v45, v85
	v_add_f32_e32 v46, v46, v86
	v_add_f32_e32 v47, v47, v87
	v_add_f32_e32 v48, v48, v88
	v_add_f32_e32 v49, v49, v89
	v_add_f32_e32 v50, v50, v90
	v_add_f32_e32 v51, v51, v91
	v_add_f32_e32 v52, v52, v92
	v_add_f32_e32 v53, v53, v93
	v_add_f32_e32 v54, v54, v94
	v_add_f32_e32 v55, v55, v95
	v_add_f32_e32 v56, v56, v96
	v_add_f32_e32 v57, v57, v97
	v_add_f32_e32 v58, v58, v98
	v_add_f32_e32 v59, v59, v99
	v_add_f32_e32 v60, v60, v100
	v_add_f32_e32 v61, v61, v101
	v_add_f32_e32 v62, v62, v102
	v_add_f32_e32 v63, v63, v103
	v_add_f32_e32 v64, v64, v104
	v_add_f32_e32 v65, v65, v105
	v_add_f32_e32 v66, v66, v106
	v_add_f32_e32 v67, v67, v107
	v_add_f32_e32 v68, v68, v108
	v_add_f32_e32 v69, v69, v109
	v_add_f32_e32 v70, v70, v110
	v_add_f32_e32 v71, v71, v111
	s_waitcnt vmcnt(0)
	v_add_f32_e32 v32, v32, v172
	v_add_f32_e32 v33, v33, v173
	v_add_f32_e32 v34, v34, v174
	v_add_f32_e32 v35, v35, v175
	v_add_f32_e32 v36, v36, v176
	v_add_f32_e32 v37, v37, v177
	v_add_f32_e32 v38, v38, v178
	v_add_f32_e32 v39, v39, v179
	v_add_f32_e32 v40, v40, v180
	v_add_f32_e32 v41, v41, v181
	v_add_f32_e32 v42, v42, v182
	v_add_f32_e32 v43, v43, v183
	v_add_f32_e32 v44, v44, v184
	v_add_f32_e32 v45, v45, v185
	v_add_f32_e32 v46, v46, v186
	v_add_f32_e32 v47, v47, v187
	v_add_f32_e32 v48, v48, v196
	v_add_f32_e32 v49, v49, v197
	v_add_f32_e32 v50, v50, v198
	v_add_f32_e32 v51, v51, v199
	v_add_f32_e32 v52, v52, v172
	v_add_f32_e32 v53, v53, v173
	v_add_f32_e32 v54, v54, v174
	v_add_f32_e32 v55, v55, v175
	v_add_f32_e32 v56, v56, v176
	v_add_f32_e32 v57, v57, v177
	v_add_f32_e32 v58, v58, v178
	v_add_f32_e32 v59, v59, v179
	v_add_f32_e32 v60, v60, v180
	v_add_f32_e32 v61, v61, v181
	v_add_f32_e32 v62, v62, v182
	v_add_f32_e32 v63, v63, v183
	v_add_f32_e32 v64, v64, v184
	v_add_f32_e32 v65, v65, v185
	v_add_f32_e32 v66, v66, v186
	v_add_f32_e32 v67, v67, v187
	v_add_f32_e32 v68, v68, v196
	v_add_f32_e32 v69, v69, v197
	v_add_f32_e32 v70, v70, v198
	v_add_f32_e32 v71, v71, v199
	s_nop 1
	global_store_dwordx4 v2, v[32:35], s[40:41]
	global_store_dwordx4 v2, v[36:39], s[40:41] offset:64
	global_store_dwordx4 v2, v[40:43], s[40:41] offset:128
	global_store_dwordx4 v2, v[44:47], s[40:41] offset:192
	global_store_dwordx4 v2, v[48:51], s[40:41] offset:256
	global_store_dwordx4 v2, v[52:55], s[46:47]
	global_store_dwordx4 v2, v[56:59], s[46:47] offset:64
	global_store_dwordx4 v2, v[60:63], s[46:47] offset:128
	global_store_dwordx4 v2, v[64:67], s[46:47] offset:192
	global_store_dwordx4 v2, v[68:71], s[46:47] offset:256
.Lmisc_bar2:
	s_waitcnt lgkmcnt(0)
	s_barrier
	s_add_i32 s24, s24, 1
	s_cmp_eq_u32 s24, 1
	s_cbranch_scc0 .Lmisc_done
	s_cmp_lt_u32 s48, 32
	s_cbranch_scc1 .Lmisc_round
